# seams 2,3,5 as barriers among the 32 workgroups of one blockIdx%8 group only (seam 4 stays grid-wide for the Z16-over-H reuse); seams 2..5 without L2 maintenance
# baseline (speedup 1.0000x reference)
; __device__ __forceinline__ void own_barrier(unsigned* cnt, unsigned G) {
;     asm volatile("s_waitcnt vmcnt(0) lgkmcnt(0)" ::: "memory");
;     __syncthreads();
;     if (threadIdx.x == 0) {
;         __builtin_amdgcn_fence(__ATOMIC_RELEASE, "agent"); asm volatile("s_waitcnt vmcnt(0)" ::: "memory");
;         unsigned target;
;         if ((G & 7u) == 0u) { target = 8u;
;             const unsigned old = __hip_atomic_fetch_add(cnt + 64 * (1 + (blockIdx.x & 7)), 1u, __ATOMIC_RELAXED, __HIP_MEMORY_SCOPE_AGENT);
;             if (old + 1u == (G >> 3)) __hip_atomic_fetch_add(cnt, 1u, __ATOMIC_RELAXED, __HIP_MEMORY_SCOPE_AGENT); }
;         else { target = G; __hip_atomic_fetch_add(cnt, 1u, __ATOMIC_RELAXED, __HIP_MEMORY_SCOPE_AGENT); }
;         unsigned spins = 0;
;         while (__hip_atomic_load(cnt, __ATOMIC_RELAXED, __HIP_MEMORY_SCOPE_AGENT) < target && ++spins < (1u << 22)) __builtin_amdgcn_s_sleep(1);
;         __builtin_amdgcn_fence(__ATOMIC_ACQUIRE, "agent"); asm volatile("s_waitcnt vmcnt(0)" ::: "memory");
;     }
;     __syncthreads();
.Lseam2_grp:
	s_and_b32 s100, s2, 7
	s_lshl_b32 s100, s100, 8
	s_add_u32 s100, s100, 0x8e02100
	v_mov_b32_e32 v1, s100
	v_mov_b32_e32 v2, 1
	global_atomic_add v2, v1, v2, s[90:91] sc0
	s_lshl_b32 s100, s2, 12
	s_add_u32 s100, s100, 0x8e10000
	v_mov_b32_e32 v1, s100
	s_waitcnt vmcnt(0)
	v_readfirstlane_b32 s100, v2
	s_cmp_eq_u32 s100, 31
	s_cbranch_scc0 .Lseam2_wait
	s_mov_b32 exec_lo, -1
	s_mov_b32 exec_hi, 0
	v_mbcnt_lo_u32_b32 v243, -1, 0
	v_lshlrev_b32_e32 v243, 15, v243
	s_and_b32 s100, s2, 7
	s_lshl_b32 s100, s100, 12
	s_add_u32 s100, s100, 0x8e10000
	v_add_u32_e32 v243, s100, v243
	v_mov_b32_e32 v244, 2
	global_store_dword v243, v244, s[90:91] sc1
	s_mov_b64 exec, 1
	s_branch .Lseam2_done

; __device__ __forceinline__ void own_barrier(unsigned* cnt, unsigned G) {
;     asm volatile("s_waitcnt vmcnt(0) lgkmcnt(0)" ::: "memory");
;     __syncthreads();
;     if (threadIdx.x == 0) {
;         __builtin_amdgcn_fence(__ATOMIC_RELEASE, "agent"); asm volatile("s_waitcnt vmcnt(0)" ::: "memory");
;         unsigned target;
;         if ((G & 7u) == 0u) { target = 8u;
;             const unsigned old = __hip_atomic_fetch_add(cnt + 64 * (1 + (blockIdx.x & 7)), 1u, __ATOMIC_RELAXED, __HIP_MEMORY_SCOPE_AGENT);
;             if (old + 1u == (G >> 3)) __hip_atomic_fetch_add(cnt, 1u, __ATOMIC_RELAXED, __HIP_MEMORY_SCOPE_AGENT); }
;         else { target = G; __hip_atomic_fetch_add(cnt, 1u, __ATOMIC_RELAXED, __HIP_MEMORY_SCOPE_AGENT); }
;         unsigned spins = 0;
;         while (__hip_atomic_load(cnt, __ATOMIC_RELAXED, __HIP_MEMORY_SCOPE_AGENT) < target && ++spins < (1u << 22)) __builtin_amdgcn_s_sleep(1);
;         __builtin_amdgcn_fence(__ATOMIC_ACQUIRE, "agent"); asm volatile("s_waitcnt vmcnt(0)" ::: "memory");
;     }
;     __syncthreads();
.Lseam3_grp:
	s_and_b32 s100, s2, 7
	s_lshl_b32 s100, s100, 8
	s_add_u32 s100, s100, 0x8e03100
	v_mov_b32_e32 v1, s100
	v_mov_b32_e32 v2, 1
	global_atomic_add v2, v1, v2, s[90:91] sc0
	s_lshl_b32 s100, s2, 12
	s_add_u32 s100, s100, 0x8e10000
	v_mov_b32_e32 v1, s100
	s_waitcnt vmcnt(0)
	v_readfirstlane_b32 s100, v2
	s_cmp_eq_u32 s100, 31
	s_cbranch_scc0 .Lseam3_wait
	s_mov_b32 exec_lo, -1
	s_mov_b32 exec_hi, 0
	v_mbcnt_lo_u32_b32 v243, -1, 0
	v_lshlrev_b32_e32 v243, 15, v243
	s_and_b32 s100, s2, 7
	s_lshl_b32 s100, s100, 12
	s_add_u32 s100, s100, 0x8e10000
	v_add_u32_e32 v243, s100, v243
	v_mov_b32_e32 v244, 3
	global_store_dword v243, v244, s[90:91] sc1
	s_mov_b64 exec, 1
	s_branch .Lseam3_done

; __device__ __forceinline__ void own_barrier(unsigned* cnt, unsigned G) {
;     asm volatile("s_waitcnt vmcnt(0) lgkmcnt(0)" ::: "memory");
;     __syncthreads();
;     if (threadIdx.x == 0) {
;         __builtin_amdgcn_fence(__ATOMIC_RELEASE, "agent"); asm volatile("s_waitcnt vmcnt(0)" ::: "memory");
;         unsigned target;
;         if ((G & 7u) == 0u) { target = 8u;
;             const unsigned old = __hip_atomic_fetch_add(cnt + 64 * (1 + (blockIdx.x & 7)), 1u, __ATOMIC_RELAXED, __HIP_MEMORY_SCOPE_AGENT);
;             if (old + 1u == (G >> 3)) __hip_atomic_fetch_add(cnt, 1u, __ATOMIC_RELAXED, __HIP_MEMORY_SCOPE_AGENT); }
;         else { target = G; __hip_atomic_fetch_add(cnt, 1u, __ATOMIC_RELAXED, __HIP_MEMORY_SCOPE_AGENT); }
;         unsigned spins = 0;
;         while (__hip_atomic_load(cnt, __ATOMIC_RELAXED, __HIP_MEMORY_SCOPE_AGENT) < target && ++spins < (1u << 22)) __builtin_amdgcn_s_sleep(1);
;         __builtin_amdgcn_fence(__ATOMIC_ACQUIRE, "agent"); asm volatile("s_waitcnt vmcnt(0)" ::: "memory");
;     }
;     __syncthreads();
.Lseam5_grp:
	s_and_b32 s100, s2, 7
	s_lshl_b32 s100, s100, 8
	s_add_u32 s100, s100, 0x8e05100
	v_mov_b32_e32 v1, s100
	v_mov_b32_e32 v2, 1
	global_atomic_add v2, v1, v2, s[90:91] sc0
	s_lshl_b32 s100, s2, 12
	s_add_u32 s100, s100, 0x8e10000
	v_mov_b32_e32 v1, s100
	s_waitcnt vmcnt(0)
	v_readfirstlane_b32 s100, v2
	s_cmp_eq_u32 s100, 31
	s_cbranch_scc0 .Lseam5_wait
	s_mov_b32 exec_lo, -1
	s_mov_b32 exec_hi, 0
	v_mbcnt_lo_u32_b32 v243, -1, 0
	v_lshlrev_b32_e32 v243, 15, v243
	s_and_b32 s100, s2, 7
	s_lshl_b32 s100, s100, 12
	s_add_u32 s100, s100, 0x8e10000
	v_add_u32_e32 v243, s100, v243
	v_mov_b32_e32 v244, 5
	global_store_dword v243, v244, s[90:91] sc1
	s_mov_b64 exec, 1
	s_branch .Lseam5_done
